# K-loop back-edge rotation only: pointer/counter bumps moved above the loop-back barrier (phase 1 untouched); otherwise v051
# speedup vs baseline: 1.0119x; 1.0022x over previous
.LBB0_836:
	s_add_u32 s19, s90, s12
	s_addc_u32 s20, s91, s13
	s_and_b64 s[16:17], s[14:15], exec
	s_cselect_b32 s17, s45, s20
	s_cselect_b32 s16, s44, s19
	s_add_u32 s19, s52, s12
	s_addc_u32 s20, s53, s13
	s_lshl_b64 s[24:25], s[40:41], 7
	s_and_b64 s[14:15], s[14:15], exec
	s_cselect_b32 s15, s93, s20
	s_cselect_b32 s14, s92, s19
	s_cselect_b32 s20, s25, s7
	s_cselect_b32 s21, s24, s6
	s_add_i32 s24, 0, 0x10000
	v_add_u32_e32 v2, s24, v252
	s_add_i32 s25, 0, 0x14000
	ds_read_b128 v[144:147], v2
	ds_read_b128 v[148:151], v2 offset:1024
	ds_read_b128 v[152:155], v2 offset:2048
	ds_read_b128 v[156:159], v2 offset:3072
	v_add_u32_e32 v2, s25, v252
	ds_read_b128 v[160:163], v2
	ds_read_b128 v[164:167], v2 offset:1024
	ds_read_b128 v[168:171], v2 offset:2048
	ds_read_b128 v[172:175], v2 offset:3072
	s_mov_b32 s19, s41
	v_lshl_add_u64 v[236:237], s[90:91], 0, v[134:135]
	s_add_i32 m0, s78, 0xc000
	ds_read_b128 v[176:179], v229
	ds_read_b128 v[180:183], v229 offset:1024
	ds_read_b128 v[184:187], v229 offset:2048
	ds_read_b128 v[204:207], v229 offset:3072
	ds_read_b128 v[208:211], v229 offset:4096
	ds_read_b128 v[212:215], v229 offset:5120
	ds_read_b128 v[224:227], v229 offset:6144
	ds_read_b128 v[216:219], v229 offset:7168
	global_load_lds_dwordx4 v[236:237], off
	v_lshl_add_u64 v[236:237], s[90:91], 0, v[4:5]
	s_add_i32 m0, s78, 0xe000
	s_nop 0
	global_load_lds_dwordx4 v[236:237], off
	s_waitcnt vmcnt(8)
	s_waitcnt lgkmcnt(0)
	s_barrier
	s_waitcnt lgkmcnt(0)
	v_mfma_f32_16x16x32_bf16 v[126:129], v[144:147], v[176:179], v[126:129]
	v_mfma_f32_16x16x32_bf16 v[130:133], v[152:155], v[176:179], v[130:133]
	v_mfma_f32_16x16x32_bf16 v[118:121], v[144:147], v[184:187], v[118:121]
	v_mfma_f32_16x16x32_bf16 v[122:125], v[152:155], v[184:187], v[122:125]
	v_mfma_f32_16x16x32_bf16 v[110:113], v[144:147], v[208:211], v[110:113]
	v_mfma_f32_16x16x32_bf16 v[114:117], v[152:155], v[208:211], v[114:117]
	v_mfma_f32_16x16x32_bf16 v[102:105], v[144:147], v[224:227], v[102:105]
	v_mfma_f32_16x16x32_bf16 v[106:109], v[152:155], v[224:227], v[106:109]
	v_mfma_f32_16x16x32_bf16 v[126:129], v[148:151], v[180:183], v[126:129]
	v_mfma_f32_16x16x32_bf16 v[130:133], v[156:159], v[180:183], v[130:133]
	v_mfma_f32_16x16x32_bf16 v[118:121], v[148:151], v[204:207], v[118:121]
	v_mfma_f32_16x16x32_bf16 v[122:125], v[156:159], v[204:207], v[122:125]
	v_mfma_f32_16x16x32_bf16 v[110:113], v[148:151], v[212:215], v[110:113]
	v_mfma_f32_16x16x32_bf16 v[114:117], v[156:159], v[212:215], v[114:117]
	v_mfma_f32_16x16x32_bf16 v[102:105], v[148:151], v[216:219], v[102:105]
	v_mfma_f32_16x16x32_bf16 v[106:109], v[156:159], v[216:219], v[106:109]
	v_mfma_f32_16x16x32_bf16 v[94:97], v[160:163], v[176:179], v[94:97]
	v_mfma_f32_16x16x32_bf16 v[98:101], v[168:171], v[176:179], v[98:101]
	v_mfma_f32_16x16x32_bf16 v[86:89], v[160:163], v[184:187], v[86:89]
	v_mfma_f32_16x16x32_bf16 v[90:93], v[168:171], v[184:187], v[90:93]
	v_mfma_f32_16x16x32_bf16 v[78:81], v[160:163], v[208:211], v[78:81]
	v_mfma_f32_16x16x32_bf16 v[82:85], v[168:171], v[208:211], v[82:85]
	v_mfma_f32_16x16x32_bf16 v[70:73], v[160:163], v[224:227], v[70:73]
	v_mfma_f32_16x16x32_bf16 v[74:77], v[168:171], v[224:227], v[74:77]
	v_mfma_f32_16x16x32_bf16 v[94:97], v[164:167], v[180:183], v[94:97]
	v_mfma_f32_16x16x32_bf16 v[98:101], v[172:175], v[180:183], v[98:101]
	v_mfma_f32_16x16x32_bf16 v[86:89], v[164:167], v[204:207], v[86:89]
	v_mfma_f32_16x16x32_bf16 v[90:93], v[172:175], v[204:207], v[90:93]
	v_mfma_f32_16x16x32_bf16 v[78:81], v[164:167], v[212:215], v[78:81]
	v_mfma_f32_16x16x32_bf16 v[82:85], v[172:175], v[212:215], v[82:85]
	v_mfma_f32_16x16x32_bf16 v[70:73], v[164:167], v[216:219], v[70:73]
	v_mfma_f32_16x16x32_bf16 v[74:77], v[172:175], v[216:219], v[74:77]
	s_barrier
	s_add_i32 s24, s24, s5
	s_mov_b32 m0, s24
	ds_read_b128 v[176:179], v229 offset:16384
	ds_read_b128 v[180:183], v229 offset:17408
	ds_read_b128 v[184:187], v229 offset:18432
	ds_read_b128 v[204:207], v229 offset:19456
	ds_read_b128 v[208:211], v229 offset:20480
	ds_read_b128 v[212:215], v229 offset:21504
	ds_read_b128 v[216:219], v229 offset:22528
	ds_read_b128 v[224:227], v229 offset:23552
	v_mov_b32_e32 v143, v3
	global_load_lds_dwordx4 v142, s[14:15]
	v_mov_b32_e32 v141, v3
	s_add_i32 m0, s24, 0x2000
	s_lshl_b64 s[18:19], s[18:19], 7
	v_lshl_add_u64 v[236:237], s[14:15], 0, v[142:143]
	v_lshl_add_u64 v[222:223], s[14:15], 0, v[140:141]
	global_load_lds_dwordx4 v140, s[14:15]
	s_add_u32 s14, s14, s18
	s_addc_u32 s15, s15, s19
	s_add_i32 s18, s25, s5
	s_mov_b32 m0, s18
	v_lshl_add_u64 v[250:251], s[16:17], 0, v[138:139]
	global_load_lds_dwordx4 v142, s[14:15]
	s_add_i32 m0, s18, 0x2000
	v_lshl_add_u64 v[232:233], s[16:17], 0, v[136:137]
	global_load_lds_dwordx4 v140, s[14:15]
	s_mov_b32 m0, s78
	v_lshl_add_u64 v[244:245], s[14:15], 0, v[142:143]
	global_load_lds_dwordx4 v[250:251], off
	s_mov_b32 m0, s87
	v_lshl_add_u64 v[246:247], s[14:15], 0, v[140:141]
	global_load_lds_dwordx4 v[232:233], off
	s_waitcnt vmcnt(8)
	s_waitcnt lgkmcnt(0)
	s_barrier
	s_waitcnt lgkmcnt(0)
	v_mfma_f32_16x16x32_bf16 v[46:49], v[144:147], v[176:179], v[46:49]
	v_mfma_f32_16x16x32_bf16 v[50:53], v[152:155], v[176:179], v[50:53]
	v_mfma_f32_16x16x32_bf16 v[38:41], v[144:147], v[184:187], v[38:41]
	v_mfma_f32_16x16x32_bf16 v[42:45], v[152:155], v[184:187], v[42:45]
	v_mfma_f32_16x16x32_bf16 v[30:33], v[144:147], v[208:211], v[30:33]
	v_mfma_f32_16x16x32_bf16 v[34:37], v[152:155], v[208:211], v[34:37]
	v_mfma_f32_16x16x32_bf16 v[22:25], v[144:147], v[216:219], v[22:25]
	v_mfma_f32_16x16x32_bf16 v[26:29], v[152:155], v[216:219], v[26:29]
	v_mfma_f32_16x16x32_bf16 v[46:49], v[148:151], v[180:183], v[46:49]
	v_mfma_f32_16x16x32_bf16 v[50:53], v[156:159], v[180:183], v[50:53]
	v_mfma_f32_16x16x32_bf16 v[38:41], v[148:151], v[204:207], v[38:41]
	v_mfma_f32_16x16x32_bf16 v[42:45], v[156:159], v[204:207], v[42:45]
	v_mfma_f32_16x16x32_bf16 v[30:33], v[148:151], v[212:215], v[30:33]
	v_mfma_f32_16x16x32_bf16 v[34:37], v[156:159], v[212:215], v[34:37]
	v_mfma_f32_16x16x32_bf16 v[22:25], v[148:151], v[224:227], v[22:25]
	v_mfma_f32_16x16x32_bf16 v[26:29], v[156:159], v[224:227], v[26:29]
	v_mfma_f32_16x16x32_bf16 v[14:17], v[160:163], v[176:179], v[14:17]
	v_mfma_f32_16x16x32_bf16 v[18:21], v[168:171], v[176:179], v[18:21]
	v_mfma_f32_16x16x32_bf16 v[6:9], v[160:163], v[184:187], v[6:9]
	v_mfma_f32_16x16x32_bf16 v[10:13], v[168:171], v[184:187], v[10:13]
	v_mfma_f32_16x16x32_bf16 v[54:57], v[160:163], v[208:211], v[54:57]
	v_mfma_f32_16x16x32_bf16 v[62:65], v[168:171], v[208:211], v[62:65]
	v_mfma_f32_16x16x32_bf16 v[58:61], v[160:163], v[216:219], v[58:61]
	v_mfma_f32_16x16x32_bf16 v[66:69], v[168:171], v[216:219], v[66:69]
	v_mfma_f32_16x16x32_bf16 v[14:17], v[164:167], v[180:183], v[14:17]
	v_mfma_f32_16x16x32_bf16 v[18:21], v[172:175], v[180:183], v[18:21]
	v_mfma_f32_16x16x32_bf16 v[6:9], v[164:167], v[204:207], v[6:9]
	v_mfma_f32_16x16x32_bf16 v[10:13], v[172:175], v[204:207], v[10:13]
	v_mfma_f32_16x16x32_bf16 v[54:57], v[164:167], v[212:215], v[54:57]
	v_mfma_f32_16x16x32_bf16 v[62:65], v[172:175], v[212:215], v[62:65]
	v_mfma_f32_16x16x32_bf16 v[58:61], v[164:167], v[224:227], v[58:61]
	v_mfma_f32_16x16x32_bf16 v[66:69], v[172:175], v[224:227], v[66:69]
	s_barrier
	s_add_i32 s18, 0, 0x18000
	v_add_u32_e32 v2, s18, v252
	s_add_i32 s19, 0, 0x1c000
	ds_read_b128 v[140:143], v2
	ds_read_b128 v[144:147], v2 offset:1024
	ds_read_b128 v[148:151], v2 offset:2048
	ds_read_b128 v[152:155], v2 offset:3072
	v_add_u32_e32 v2, s19, v252
	ds_read_b128 v[156:159], v2
	ds_read_b128 v[160:163], v2 offset:1024
	ds_read_b128 v[164:167], v2 offset:2048
	ds_read_b128 v[168:171], v2 offset:3072
	s_add_u32 s14, s16, s21
	s_addc_u32 s15, s17, s20
	s_mov_b32 m0, s79
	v_lshl_add_u64 v[138:139], s[14:15], 0, v[138:139]
	ds_read_b128 v[172:175], v229 offset:32768
	ds_read_b128 v[176:179], v229 offset:33792
	ds_read_b128 v[180:183], v229 offset:34816
	ds_read_b128 v[184:187], v229 offset:35840
	ds_read_b128 v[204:207], v229 offset:36864
	ds_read_b128 v[208:211], v229 offset:37888
	ds_read_b128 v[212:215], v229 offset:38912
	ds_read_b128 v[216:219], v229 offset:39936
	global_load_lds_dwordx4 v[138:139], off
	v_lshl_add_u64 v[136:137], s[14:15], 0, v[136:137]
	s_mov_b32 m0, s34
	s_nop 0
	global_load_lds_dwordx4 v[136:137], off
	s_waitcnt vmcnt(8)
	s_waitcnt lgkmcnt(0)
	s_barrier
	s_waitcnt lgkmcnt(0)
	v_mfma_f32_16x16x32_bf16 v[126:129], v[140:143], v[172:175], v[126:129]
	v_mfma_f32_16x16x32_bf16 v[130:133], v[148:151], v[172:175], v[130:133]
	v_mfma_f32_16x16x32_bf16 v[118:121], v[140:143], v[180:183], v[118:121]
	v_mfma_f32_16x16x32_bf16 v[122:125], v[148:151], v[180:183], v[122:125]
	v_mfma_f32_16x16x32_bf16 v[110:113], v[140:143], v[204:207], v[110:113]
	v_mfma_f32_16x16x32_bf16 v[114:117], v[148:151], v[204:207], v[114:117]
	v_mfma_f32_16x16x32_bf16 v[102:105], v[140:143], v[212:215], v[102:105]
	v_mfma_f32_16x16x32_bf16 v[106:109], v[148:151], v[212:215], v[106:109]
	v_mfma_f32_16x16x32_bf16 v[126:129], v[144:147], v[176:179], v[126:129]
	v_mfma_f32_16x16x32_bf16 v[130:133], v[152:155], v[176:179], v[130:133]
	v_mfma_f32_16x16x32_bf16 v[118:121], v[144:147], v[184:187], v[118:121]
	v_mfma_f32_16x16x32_bf16 v[122:125], v[152:155], v[184:187], v[122:125]
	v_mfma_f32_16x16x32_bf16 v[110:113], v[144:147], v[208:211], v[110:113]
	v_mfma_f32_16x16x32_bf16 v[114:117], v[152:155], v[208:211], v[114:117]
	v_mfma_f32_16x16x32_bf16 v[102:105], v[144:147], v[216:219], v[102:105]
	v_mfma_f32_16x16x32_bf16 v[106:109], v[152:155], v[216:219], v[106:109]
	v_mfma_f32_16x16x32_bf16 v[94:97], v[156:159], v[172:175], v[94:97]
	v_mfma_f32_16x16x32_bf16 v[98:101], v[164:167], v[172:175], v[98:101]
	v_mfma_f32_16x16x32_bf16 v[86:89], v[156:159], v[180:183], v[86:89]
	v_mfma_f32_16x16x32_bf16 v[90:93], v[164:167], v[180:183], v[90:93]
	v_mfma_f32_16x16x32_bf16 v[78:81], v[156:159], v[204:207], v[78:81]
	v_mfma_f32_16x16x32_bf16 v[82:85], v[164:167], v[204:207], v[82:85]
	v_mfma_f32_16x16x32_bf16 v[70:73], v[156:159], v[212:215], v[70:73]
	v_mfma_f32_16x16x32_bf16 v[74:77], v[164:167], v[212:215], v[74:77]
	v_mfma_f32_16x16x32_bf16 v[94:97], v[160:163], v[176:179], v[94:97]
	v_mfma_f32_16x16x32_bf16 v[98:101], v[168:171], v[176:179], v[98:101]
	v_mfma_f32_16x16x32_bf16 v[86:89], v[160:163], v[184:187], v[86:89]
	v_mfma_f32_16x16x32_bf16 v[90:93], v[168:171], v[184:187], v[90:93]
	v_mfma_f32_16x16x32_bf16 v[78:81], v[160:163], v[208:211], v[78:81]
	v_mfma_f32_16x16x32_bf16 v[82:85], v[168:171], v[208:211], v[82:85]
	v_mfma_f32_16x16x32_bf16 v[70:73], v[160:163], v[216:219], v[70:73]
	v_mfma_f32_16x16x32_bf16 v[74:77], v[168:171], v[216:219], v[74:77]
	s_barrier
	s_add_i32 s14, s18, s5
	v_lshl_add_u64 v[216:217], v[236:237], 0, s[60:61]
	s_mov_b32 m0, s14
	ds_read_b128 v[136:139], v229 offset:49152
	ds_read_b128 v[172:175], v229 offset:50176
	ds_read_b128 v[176:179], v229 offset:51200
	ds_read_b128 v[180:183], v229 offset:52224
	ds_read_b128 v[184:187], v229 offset:53248
	ds_read_b128 v[204:207], v229 offset:54272
	ds_read_b128 v[208:211], v229 offset:55296
	ds_read_b128 v[212:215], v229 offset:56320
	global_load_lds_dwordx4 v[216:217], off
	v_lshl_add_u64 v[216:217], v[222:223], 0, s[60:61]
	s_add_i32 m0, s14, 0x2000
	s_add_i32 s14, s19, s5
	global_load_lds_dwordx4 v[216:217], off
	v_lshl_add_u64 v[216:217], v[244:245], 0, s[60:61]
	s_mov_b32 m0, s14
	s_nop 0
	global_load_lds_dwordx4 v[216:217], off
	v_lshl_add_u64 v[216:217], v[246:247], 0, s[60:61]
	s_add_i32 m0, s14, 0x2000
	s_nop 0
	global_load_lds_dwordx4 v[216:217], off
	v_lshl_add_u64 v[216:217], v[250:251], 0, s[60:61]
	s_mov_b32 m0, s35
	s_nop 0
	global_load_lds_dwordx4 v[216:217], off
	v_lshl_add_u64 v[216:217], v[232:233], 0, s[60:61]
	s_mov_b32 m0, s46
	s_nop 0
	global_load_lds_dwordx4 v[216:217], off
	s_waitcnt vmcnt(8)
	s_waitcnt lgkmcnt(0)
	s_barrier
	s_waitcnt lgkmcnt(0)
	v_mfma_f32_16x16x32_bf16 v[46:49], v[140:143], v[136:139], v[46:49]
	v_mfma_f32_16x16x32_bf16 v[50:53], v[148:151], v[136:139], v[50:53]
	v_mfma_f32_16x16x32_bf16 v[38:41], v[140:143], v[176:179], v[38:41]
	v_mfma_f32_16x16x32_bf16 v[42:45], v[148:151], v[176:179], v[42:45]
	v_mfma_f32_16x16x32_bf16 v[30:33], v[140:143], v[184:187], v[30:33]
	v_mfma_f32_16x16x32_bf16 v[34:37], v[148:151], v[184:187], v[34:37]
	v_mfma_f32_16x16x32_bf16 v[22:25], v[140:143], v[208:211], v[22:25]
	v_mfma_f32_16x16x32_bf16 v[26:29], v[148:151], v[208:211], v[26:29]
	v_mfma_f32_16x16x32_bf16 v[46:49], v[144:147], v[172:175], v[46:49]
	v_mfma_f32_16x16x32_bf16 v[50:53], v[152:155], v[172:175], v[50:53]
	v_mfma_f32_16x16x32_bf16 v[38:41], v[144:147], v[180:183], v[38:41]
	v_mfma_f32_16x16x32_bf16 v[42:45], v[152:155], v[180:183], v[42:45]
	v_mfma_f32_16x16x32_bf16 v[30:33], v[144:147], v[204:207], v[30:33]
	v_mfma_f32_16x16x32_bf16 v[34:37], v[152:155], v[204:207], v[34:37]
	v_mfma_f32_16x16x32_bf16 v[22:25], v[144:147], v[212:215], v[22:25]
	v_mfma_f32_16x16x32_bf16 v[26:29], v[152:155], v[212:215], v[26:29]
	v_mfma_f32_16x16x32_bf16 v[14:17], v[156:159], v[136:139], v[14:17]
	v_mfma_f32_16x16x32_bf16 v[18:21], v[164:167], v[136:139], v[18:21]
	v_mfma_f32_16x16x32_bf16 v[6:9], v[156:159], v[176:179], v[6:9]
	v_mfma_f32_16x16x32_bf16 v[10:13], v[164:167], v[176:179], v[10:13]
	v_mfma_f32_16x16x32_bf16 v[54:57], v[156:159], v[184:187], v[54:57]
	v_mfma_f32_16x16x32_bf16 v[62:65], v[164:167], v[184:187], v[62:65]
	v_mfma_f32_16x16x32_bf16 v[58:61], v[156:159], v[208:211], v[58:61]
	v_mfma_f32_16x16x32_bf16 v[66:69], v[164:167], v[208:211], v[66:69]
	v_mfma_f32_16x16x32_bf16 v[14:17], v[160:163], v[172:175], v[14:17]
	v_mfma_f32_16x16x32_bf16 v[18:21], v[168:171], v[172:175], v[18:21]
	v_mfma_f32_16x16x32_bf16 v[6:9], v[160:163], v[180:183], v[6:9]
	v_mfma_f32_16x16x32_bf16 v[10:13], v[168:171], v[180:183], v[10:13]
	v_mfma_f32_16x16x32_bf16 v[54:57], v[160:163], v[204:207], v[54:57]
	v_mfma_f32_16x16x32_bf16 v[62:65], v[168:171], v[204:207], v[62:65]
	v_mfma_f32_16x16x32_bf16 v[58:61], v[160:163], v[212:215], v[58:61]
	v_mfma_f32_16x16x32_bf16 v[66:69], v[168:171], v[212:215], v[66:69]
	s_add_i32 s14, s63, 2
	s_add_u32 s12, s12, 0x100
	s_addc_u32 s13, s13, 0
	v_lshl_add_u64 v[4:5], v[4:5], 0, s[68:69]
	v_lshl_add_u64 v[134:135], v[134:135], 0, s[68:69]
	s_cmp_ge_i32 s63, s47
	s_barrier
	s_cbranch_scc1 .LBB0_857
	s_mov_b32 s63, s14
	s_branch .LBB0_813
